# item_sg row loop unrolled x8: the loads of 8 rows are in flight per wave before one wait, instead of one memory round trip per row
# speedup vs baseline: 1.0033x; 1.0015x over previous
; DI void item_sg(const Params& p, int l, int L, int item, const bf16_t* __restrict__ z, bf16_t* __restrict__ sg) {
;     ...
;   for (int i = w; i < 256; i += 4) {
;     const int row = item * 256 + i;
;     const int t = row % L;
;     const bf16_t* zr = z + (size_t)row * ZC + 1664 + 2 * lane;
;     const unsigned c = *(const unsigned*)zr;
;     const unsigned pv = (t > 0) ? *(const unsigned*)(zr - ZC) : 0u;
;     const unsigned nv = (t < L - 1) ? *(const unsigned*)(zr + ZC) : 0u;
.LBB0_406:
	v_add_u32_e32 v168, v10, v11
	v_sub_u32_e32 v175, 0, v168
	v_ashrrev_i32_e32 v169, 31, v168
	v_max_i32_e32 v168, v168, v175
	v_mul_hi_u32 v175, v168, v224
	v_mul_lo_u32 v175, v175, s25
	v_sub_u32_e32 v168, v168, v175
	v_cmp_le_u32_e32 vcc, s25, v168
	v_subrev_u32_e32 v175, s25, v168
	v_mov_b32_e32 v174, 0
	v_cndmask_b32_e32 v168, v168, v175, vcc
	v_cmp_le_u32_e32 vcc, s25, v168
	v_subrev_u32_e32 v175, s25, v168
	s_nop 0
	v_cndmask_b32_e32 v168, v168, v175, vcc
	v_xor_b32_e32 v168, v168, v169
	v_sub_u32_e32 v175, v168, v169
	v_lshl_add_u64 v[168:169], v[2:3], 0, v[128:129]
	v_add_co_u32_e32 v170, vcc, 0xe348000, v168
	s_nop 1
	v_addc_co_u32_e32 v171, vcc, 0, v169, vcc
	global_load_dword v170, v[170:171], off offset:3328
	v_cmp_lt_i32_e32 vcc, 0, v175
	v_mov_b32_e32 v171, 0
	s_and_saveexec_b64 s[10:11], vcc
	v_add_co_u32_e32 v172, vcc, 0xe347000, v168
	s_nop 1
	v_addc_co_u32_e32 v173, vcc, 0, v169, vcc
	global_load_dword v171, v[172:173], off offset:768
	s_or_b64 exec, exec, s[10:11]
	v_cmp_gt_i32_e32 vcc, s41, v175
	s_and_saveexec_b64 s[10:11], vcc
	v_add_co_u32_e32 v168, vcc, 0xe34a000, v168
	s_nop 1
	v_addc_co_u32_e32 v169, vcc, 0, v169, vcc
	global_load_dword v174, v[168:169], off offset:1792
	s_or_b64 exec, exec, s[10:11]
	v_add_u32_e32 v176, v10, v11
	v_add_u32_e32 v176, 4, v176
	v_sub_u32_e32 v183, 0, v176
	v_ashrrev_i32_e32 v177, 31, v176
	v_max_i32_e32 v176, v176, v183
	v_mul_hi_u32 v183, v176, v224
	v_mul_lo_u32 v183, v183, s25
	v_sub_u32_e32 v176, v176, v183
	v_cmp_le_u32_e32 vcc, s25, v176
	v_subrev_u32_e32 v183, s25, v176
	v_mov_b32_e32 v182, 0
	v_cndmask_b32_e32 v176, v176, v183, vcc
	v_cmp_le_u32_e32 vcc, s25, v176
	v_subrev_u32_e32 v183, s25, v176
	s_nop 0
	v_cndmask_b32_e32 v176, v176, v183, vcc
	v_xor_b32_e32 v176, v176, v177
	v_sub_u32_e32 v183, v176, v177
	v_lshl_add_u64 v[176:177], v[2:3], 0, v[128:129]
	s_mov_b64 s[100:101], 0x6800
	v_lshl_add_u64 v[176:177], v[176:177], 0, s[100:101]
	v_add_co_u32_e32 v178, vcc, 0xe348000, v176
	s_nop 1
	v_addc_co_u32_e32 v179, vcc, 0, v177, vcc
	global_load_dword v178, v[178:179], off offset:3328
	v_cmp_lt_i32_e32 vcc, 0, v183
	v_mov_b32_e32 v179, 0
	s_and_saveexec_b64 s[10:11], vcc
	v_add_co_u32_e32 v180, vcc, 0xe347000, v176
	s_nop 1
	v_addc_co_u32_e32 v181, vcc, 0, v177, vcc
	global_load_dword v179, v[180:181], off offset:768
	s_or_b64 exec, exec, s[10:11]
	v_cmp_gt_i32_e32 vcc, s41, v183
	s_and_saveexec_b64 s[10:11], vcc
	v_add_co_u32_e32 v176, vcc, 0xe34a000, v176
	s_nop 1
	v_addc_co_u32_e32 v177, vcc, 0, v177, vcc
	global_load_dword v182, v[176:177], off offset:1792
	s_or_b64 exec, exec, s[10:11]
	v_add_u32_e32 v184, v10, v11
	v_add_u32_e32 v184, 8, v184
	v_sub_u32_e32 v191, 0, v184
	v_ashrrev_i32_e32 v185, 31, v184
	v_max_i32_e32 v184, v184, v191
	v_mul_hi_u32 v191, v184, v224
	v_mul_lo_u32 v191, v191, s25
	v_sub_u32_e32 v184, v184, v191
	v_cmp_le_u32_e32 vcc, s25, v184
	v_subrev_u32_e32 v191, s25, v184
	v_mov_b32_e32 v190, 0
	v_cndmask_b32_e32 v184, v184, v191, vcc
	v_cmp_le_u32_e32 vcc, s25, v184
	v_subrev_u32_e32 v191, s25, v184
	s_nop 0
	v_cndmask_b32_e32 v184, v184, v191, vcc
	v_xor_b32_e32 v184, v184, v185
	v_sub_u32_e32 v191, v184, v185
	v_lshl_add_u64 v[184:185], v[2:3], 0, v[128:129]
	s_mov_b64 s[100:101], 0xd000
	v_lshl_add_u64 v[184:185], v[184:185], 0, s[100:101]
	v_add_co_u32_e32 v186, vcc, 0xe348000, v184
	s_nop 1
	v_addc_co_u32_e32 v187, vcc, 0, v185, vcc
	global_load_dword v186, v[186:187], off offset:3328
	v_cmp_lt_i32_e32 vcc, 0, v191
	v_mov_b32_e32 v187, 0
	s_and_saveexec_b64 s[10:11], vcc
	v_add_co_u32_e32 v188, vcc, 0xe347000, v184
	s_nop 1
	v_addc_co_u32_e32 v189, vcc, 0, v185, vcc
	global_load_dword v187, v[188:189], off offset:768
	s_or_b64 exec, exec, s[10:11]
	v_cmp_gt_i32_e32 vcc, s41, v191
	s_and_saveexec_b64 s[10:11], vcc
	v_add_co_u32_e32 v184, vcc, 0xe34a000, v184
	s_nop 1
	v_addc_co_u32_e32 v185, vcc, 0, v185, vcc
	global_load_dword v190, v[184:185], off offset:1792
	s_or_b64 exec, exec, s[10:11]
	v_add_u32_e32 v192, v10, v11
	v_add_u32_e32 v192, 12, v192
	v_sub_u32_e32 v199, 0, v192
	v_ashrrev_i32_e32 v193, 31, v192
	v_max_i32_e32 v192, v192, v199
	v_mul_hi_u32 v199, v192, v224
	v_mul_lo_u32 v199, v199, s25
	v_sub_u32_e32 v192, v192, v199
	v_cmp_le_u32_e32 vcc, s25, v192
	v_subrev_u32_e32 v199, s25, v192
	v_mov_b32_e32 v198, 0
	v_cndmask_b32_e32 v192, v192, v199, vcc
	v_cmp_le_u32_e32 vcc, s25, v192
	v_subrev_u32_e32 v199, s25, v192
	s_nop 0
	v_cndmask_b32_e32 v192, v192, v199, vcc
	v_xor_b32_e32 v192, v192, v193
	v_sub_u32_e32 v199, v192, v193
	v_lshl_add_u64 v[192:193], v[2:3], 0, v[128:129]
	s_mov_b64 s[100:101], 0x13800
	v_lshl_add_u64 v[192:193], v[192:193], 0, s[100:101]
	v_add_co_u32_e32 v194, vcc, 0xe348000, v192
	s_nop 1
	v_addc_co_u32_e32 v195, vcc, 0, v193, vcc
	global_load_dword v194, v[194:195], off offset:3328
	v_cmp_lt_i32_e32 vcc, 0, v199
	v_mov_b32_e32 v195, 0
	s_and_saveexec_b64 s[10:11], vcc
	v_add_co_u32_e32 v196, vcc, 0xe347000, v192
	s_nop 1
	v_addc_co_u32_e32 v197, vcc, 0, v193, vcc
	global_load_dword v195, v[196:197], off offset:768
	s_or_b64 exec, exec, s[10:11]
	v_cmp_gt_i32_e32 vcc, s41, v199
	s_and_saveexec_b64 s[10:11], vcc
	v_add_co_u32_e32 v192, vcc, 0xe34a000, v192
	s_nop 1
	v_addc_co_u32_e32 v193, vcc, 0, v193, vcc
	global_load_dword v198, v[192:193], off offset:1792
	s_or_b64 exec, exec, s[10:11]
	v_add_u32_e32 v200, v10, v11
	v_add_u32_e32 v200, 16, v200
	v_sub_u32_e32 v207, 0, v200
	v_ashrrev_i32_e32 v201, 31, v200
	v_max_i32_e32 v200, v200, v207
	v_mul_hi_u32 v207, v200, v224
	v_mul_lo_u32 v207, v207, s25
	v_sub_u32_e32 v200, v200, v207
	v_cmp_le_u32_e32 vcc, s25, v200
	v_subrev_u32_e32 v207, s25, v200
; DI void item_sg(const Params& p, int l, int L, int item, const bf16_t* __restrict__ z, bf16_t* __restrict__ sg) {
;     ...
;   for (int i = w; i < 256; i += 4) {
;     const int row = item * 256 + i;
;     const int t = row % L;
;     const bf16_t* zr = z + (size_t)row * ZC + 1664 + 2 * lane;
;     const unsigned c = *(const unsigned*)zr;
;     const unsigned pv = (t > 0) ? *(const unsigned*)(zr - ZC) : 0u;
;     const unsigned nv = (t < L - 1) ? *(const unsigned*)(zr + ZC) : 0u;
	v_mov_b32_e32 v206, 0
	v_cndmask_b32_e32 v200, v200, v207, vcc
	v_cmp_le_u32_e32 vcc, s25, v200
	v_subrev_u32_e32 v207, s25, v200
	s_nop 0
	v_cndmask_b32_e32 v200, v200, v207, vcc
	v_xor_b32_e32 v200, v200, v201
	v_sub_u32_e32 v207, v200, v201
	v_lshl_add_u64 v[200:201], v[2:3], 0, v[128:129]
	s_mov_b64 s[100:101], 0x1a000
	v_lshl_add_u64 v[200:201], v[200:201], 0, s[100:101]
	v_add_co_u32_e32 v202, vcc, 0xe348000, v200
	s_nop 1
	v_addc_co_u32_e32 v203, vcc, 0, v201, vcc
	global_load_dword v202, v[202:203], off offset:3328
	v_cmp_lt_i32_e32 vcc, 0, v207
	v_mov_b32_e32 v203, 0
	s_and_saveexec_b64 s[10:11], vcc
	v_add_co_u32_e32 v204, vcc, 0xe347000, v200
	s_nop 1
	v_addc_co_u32_e32 v205, vcc, 0, v201, vcc
	global_load_dword v203, v[204:205], off offset:768
	s_or_b64 exec, exec, s[10:11]
	v_cmp_gt_i32_e32 vcc, s41, v207
	s_and_saveexec_b64 s[10:11], vcc
	v_add_co_u32_e32 v200, vcc, 0xe34a000, v200
	s_nop 1
	v_addc_co_u32_e32 v201, vcc, 0, v201, vcc
	global_load_dword v206, v[200:201], off offset:1792
	s_or_b64 exec, exec, s[10:11]
	v_add_u32_e32 v228, v10, v11
	v_add_u32_e32 v228, 20, v228
	v_sub_u32_e32 v235, 0, v228
	v_ashrrev_i32_e32 v229, 31, v228
	v_max_i32_e32 v228, v228, v235
	v_mul_hi_u32 v235, v228, v224
	v_mul_lo_u32 v235, v235, s25
	v_sub_u32_e32 v228, v228, v235
	v_cmp_le_u32_e32 vcc, s25, v228
	v_subrev_u32_e32 v235, s25, v228
	v_mov_b32_e32 v234, 0
	v_cndmask_b32_e32 v228, v228, v235, vcc
	v_cmp_le_u32_e32 vcc, s25, v228
	v_subrev_u32_e32 v235, s25, v228
	s_nop 0
	v_cndmask_b32_e32 v228, v228, v235, vcc
	v_xor_b32_e32 v228, v228, v229
	v_sub_u32_e32 v235, v228, v229
	v_lshl_add_u64 v[228:229], v[2:3], 0, v[128:129]
	s_mov_b64 s[100:101], 0x20800
	v_lshl_add_u64 v[228:229], v[228:229], 0, s[100:101]
	v_add_co_u32_e32 v230, vcc, 0xe348000, v228
	s_nop 1
	v_addc_co_u32_e32 v231, vcc, 0, v229, vcc
	global_load_dword v230, v[230:231], off offset:3328
	v_cmp_lt_i32_e32 vcc, 0, v235
	v_mov_b32_e32 v231, 0
	s_and_saveexec_b64 s[10:11], vcc
	v_add_co_u32_e32 v232, vcc, 0xe347000, v228
	s_nop 1
	v_addc_co_u32_e32 v233, vcc, 0, v229, vcc
	global_load_dword v231, v[232:233], off offset:768
	s_or_b64 exec, exec, s[10:11]
	v_cmp_gt_i32_e32 vcc, s41, v235
	s_and_saveexec_b64 s[10:11], vcc
	v_add_co_u32_e32 v228, vcc, 0xe34a000, v228
	s_nop 1
	v_addc_co_u32_e32 v229, vcc, 0, v229, vcc
	global_load_dword v234, v[228:229], off offset:1792
	s_or_b64 exec, exec, s[10:11]
	v_add_u32_e32 v236, v10, v11
	v_add_u32_e32 v236, 24, v236
	v_sub_u32_e32 v243, 0, v236
	v_ashrrev_i32_e32 v237, 31, v236
	v_max_i32_e32 v236, v236, v243
	v_mul_hi_u32 v243, v236, v224
	v_mul_lo_u32 v243, v243, s25
	v_sub_u32_e32 v236, v236, v243
	v_cmp_le_u32_e32 vcc, s25, v236
	v_subrev_u32_e32 v243, s25, v236
	v_mov_b32_e32 v242, 0
	v_cndmask_b32_e32 v236, v236, v243, vcc
	v_cmp_le_u32_e32 vcc, s25, v236
	v_subrev_u32_e32 v243, s25, v236
	s_nop 0
	v_cndmask_b32_e32 v236, v236, v243, vcc
	v_xor_b32_e32 v236, v236, v237
	v_sub_u32_e32 v243, v236, v237
	v_lshl_add_u64 v[236:237], v[2:3], 0, v[128:129]
	s_mov_b64 s[100:101], 0x27000
	v_lshl_add_u64 v[236:237], v[236:237], 0, s[100:101]
	v_add_co_u32_e32 v238, vcc, 0xe348000, v236
	s_nop 1
	v_addc_co_u32_e32 v239, vcc, 0, v237, vcc
	global_load_dword v238, v[238:239], off offset:3328
	v_cmp_lt_i32_e32 vcc, 0, v243
	v_mov_b32_e32 v239, 0
	s_and_saveexec_b64 s[10:11], vcc
	v_add_co_u32_e32 v240, vcc, 0xe347000, v236
	s_nop 1
	v_addc_co_u32_e32 v241, vcc, 0, v237, vcc
	global_load_dword v239, v[240:241], off offset:768
	s_or_b64 exec, exec, s[10:11]
	v_cmp_gt_i32_e32 vcc, s41, v243
	s_and_saveexec_b64 s[10:11], vcc
	v_add_co_u32_e32 v236, vcc, 0xe34a000, v236
	s_nop 1
	v_addc_co_u32_e32 v237, vcc, 0, v237, vcc
	global_load_dword v242, v[236:237], off offset:1792
	s_or_b64 exec, exec, s[10:11]
	v_add_u32_e32 v244, v10, v11
	v_add_u32_e32 v244, 28, v244
	v_sub_u32_e32 v251, 0, v244
	v_ashrrev_i32_e32 v245, 31, v244
	v_max_i32_e32 v244, v244, v251
	v_mul_hi_u32 v251, v244, v224
	v_mul_lo_u32 v251, v251, s25
	v_sub_u32_e32 v244, v244, v251
	v_cmp_le_u32_e32 vcc, s25, v244
	v_subrev_u32_e32 v251, s25, v244
	v_mov_b32_e32 v250, 0
	v_cndmask_b32_e32 v244, v244, v251, vcc
	v_cmp_le_u32_e32 vcc, s25, v244
	v_subrev_u32_e32 v251, s25, v244
	s_nop 0
	v_cndmask_b32_e32 v244, v244, v251, vcc
	v_xor_b32_e32 v244, v244, v245
	v_sub_u32_e32 v251, v244, v245
	v_lshl_add_u64 v[244:245], v[2:3], 0, v[128:129]
	s_mov_b64 s[100:101], 0x2d800
	v_lshl_add_u64 v[244:245], v[244:245], 0, s[100:101]
	v_add_co_u32_e32 v246, vcc, 0xe348000, v244
	s_nop 1
	v_addc_co_u32_e32 v247, vcc, 0, v245, vcc
	global_load_dword v246, v[246:247], off offset:3328
	v_cmp_lt_i32_e32 vcc, 0, v251
	v_mov_b32_e32 v247, 0
	s_and_saveexec_b64 s[10:11], vcc
	v_add_co_u32_e32 v248, vcc, 0xe347000, v244
	s_nop 1
	v_addc_co_u32_e32 v249, vcc, 0, v245, vcc
	global_load_dword v247, v[248:249], off offset:768
	s_or_b64 exec, exec, s[10:11]
	v_cmp_gt_i32_e32 vcc, s41, v251
	s_and_saveexec_b64 s[10:11], vcc
	v_add_co_u32_e32 v244, vcc, 0xe34a000, v244
	s_nop 1
	v_addc_co_u32_e32 v245, vcc, 0, v245, vcc
	global_load_dword v250, v[244:245], off offset:1792
	s_or_b64 exec, exec, s[10:11]
	s_waitcnt vmcnt(0)
; DI unsigned pack2(float lo, float hi) { const f32x2 v = {lo, hi}; const bf16x2_t b = __builtin_convertvector(v, bf16x2_t); return __builtin_bit_cast(unsigned, b); }
; DI float lo2f(unsigned u) { return __uint_as_float(u << 16); }
; DI float hi2f(unsigned u) { return __uint_as_float(u & 0xffff0000u); }
; DI float sigmoidf_(float x) { return rcp_(1.0f + __expf(-x)); }
; DI void item_sg(const Params& p, int l, int L, int item, const bf16_t* __restrict__ z, bf16_t* __restrict__ sg) {
;     ...
;     const float ca = lo2f(c), cb = hi2f(c);
;     const float ga = ca + m0a * (lo2f(pv) - ca) + m1a * (lo2f(nv) - ca);
;     const float gb = cb + m0b * (hi2f(pv) - cb) + m1b * (hi2f(nv) - cb);
;     *(unsigned*)(sg + (size_t)row * 128 + 2 * lane) = pack2(sigmoidf_(ga), sigmoidf_(gb));
	v_lshlrev_b32_e32 v168, 16, v170
	v_lshlrev_b32_e32 v173, 16, v174
	v_lshlrev_b32_e32 v172, 16, v171
	v_pk_add_f32 v[172:173], v[172:173], v[168:169] op_sel_hi:[1,0] neg_lo:[0,1] neg_hi:[0,1]
	v_and_b32_e32 v170, 0xffff0000, v170
	v_pk_mul_f32 v[172:173], v[0:1], v[172:173]
	v_and_b32_e32 v169, 0xffff0000, v174
	v_add_f32_e32 v168, v172, v168
	v_add_f32_e32 v175, v168, v173
	v_and_b32_e32 v168, 0xffff0000, v171
	v_pk_add_f32 v[168:169], v[168:169], v[170:171] op_sel_hi:[1,0] neg_lo:[0,1] neg_hi:[0,1]
	v_pk_mul_f32 v[168:169], v[6:7], v[168:169]
	v_add_f32_e32 v168, v168, v170
	v_add_f32_e32 v168, v168, v169
	v_mul_f32_e32 v169, 0xbfb8aa3b, v175
	v_mul_f32_e32 v168, 0xbfb8aa3b, v168
	v_exp_f32_e32 v169, v169
	v_exp_f32_e32 v168, v168
	v_add_f32_e32 v169, 1.0, v169
	v_add_f32_e32 v168, 1.0, v168
	v_rcp_f32_e32 v169, v169
	v_rcp_f32_e32 v168, v168
	s_nop 0
	v_cvt_pk_bf16_f32 v174, v169, v168
	v_lshl_add_u64 v[168:169], v[4:5], 0, v[128:129]
	global_store_dword v[168:169], v174, off
	v_lshlrev_b32_e32 v176, 16, v178
	v_lshlrev_b32_e32 v181, 16, v182
	v_lshlrev_b32_e32 v180, 16, v179
	v_pk_add_f32 v[180:181], v[180:181], v[176:177] op_sel_hi:[1,0] neg_lo:[0,1] neg_hi:[0,1]
	v_and_b32_e32 v178, 0xffff0000, v178
	v_pk_mul_f32 v[180:181], v[0:1], v[180:181]
	v_and_b32_e32 v177, 0xffff0000, v182
	v_add_f32_e32 v176, v180, v176
	v_add_f32_e32 v183, v176, v181
	v_and_b32_e32 v176, 0xffff0000, v179
	v_pk_add_f32 v[176:177], v[176:177], v[178:179] op_sel_hi:[1,0] neg_lo:[0,1] neg_hi:[0,1]
	v_pk_mul_f32 v[176:177], v[6:7], v[176:177]
	v_add_f32_e32 v176, v176, v178
	v_add_f32_e32 v176, v176, v177
	v_mul_f32_e32 v177, 0xbfb8aa3b, v183
	v_mul_f32_e32 v176, 0xbfb8aa3b, v176
	v_exp_f32_e32 v177, v177
	v_exp_f32_e32 v176, v176
	v_add_f32_e32 v177, 1.0, v177
	v_add_f32_e32 v176, 1.0, v176
	v_rcp_f32_e32 v177, v177
	v_rcp_f32_e32 v176, v176
	s_nop 0
	v_cvt_pk_bf16_f32 v182, v177, v176
	v_lshl_add_u64 v[176:177], v[4:5], 0, v[128:129]
	s_mov_b64 s[100:101], 0x400
	v_lshl_add_u64 v[176:177], v[176:177], 0, s[100:101]
	global_store_dword v[176:177], v182, off
	v_lshlrev_b32_e32 v184, 16, v186
	v_lshlrev_b32_e32 v189, 16, v190
	v_lshlrev_b32_e32 v188, 16, v187
	v_pk_add_f32 v[188:189], v[188:189], v[184:185] op_sel_hi:[1,0] neg_lo:[0,1] neg_hi:[0,1]
	v_and_b32_e32 v186, 0xffff0000, v186
	v_pk_mul_f32 v[188:189], v[0:1], v[188:189]
	v_and_b32_e32 v185, 0xffff0000, v190
	v_add_f32_e32 v184, v188, v184
	v_add_f32_e32 v191, v184, v189
	v_and_b32_e32 v184, 0xffff0000, v187
	v_pk_add_f32 v[184:185], v[184:185], v[186:187] op_sel_hi:[1,0] neg_lo:[0,1] neg_hi:[0,1]
	v_pk_mul_f32 v[184:185], v[6:7], v[184:185]
	v_add_f32_e32 v184, v184, v186
	v_add_f32_e32 v184, v184, v185
	v_mul_f32_e32 v185, 0xbfb8aa3b, v191
	v_mul_f32_e32 v184, 0xbfb8aa3b, v184
	v_exp_f32_e32 v185, v185
	v_exp_f32_e32 v184, v184
	v_add_f32_e32 v185, 1.0, v185
	v_add_f32_e32 v184, 1.0, v184
	v_rcp_f32_e32 v185, v185
	v_rcp_f32_e32 v184, v184
	s_nop 0
	v_cvt_pk_bf16_f32 v190, v185, v184
	v_lshl_add_u64 v[184:185], v[4:5], 0, v[128:129]
	s_mov_b64 s[100:101], 0x800
	v_lshl_add_u64 v[184:185], v[184:185], 0, s[100:101]
	global_store_dword v[184:185], v190, off
	v_lshlrev_b32_e32 v192, 16, v194
	v_lshlrev_b32_e32 v197, 16, v198
	v_lshlrev_b32_e32 v196, 16, v195
	v_pk_add_f32 v[196:197], v[196:197], v[192:193] op_sel_hi:[1,0] neg_lo:[0,1] neg_hi:[0,1]
	v_and_b32_e32 v194, 0xffff0000, v194
	v_pk_mul_f32 v[196:197], v[0:1], v[196:197]
	v_and_b32_e32 v193, 0xffff0000, v198
	v_add_f32_e32 v192, v196, v192
	v_add_f32_e32 v199, v192, v197
	v_and_b32_e32 v192, 0xffff0000, v195
	v_pk_add_f32 v[192:193], v[192:193], v[194:195] op_sel_hi:[1,0] neg_lo:[0,1] neg_hi:[0,1]
	v_pk_mul_f32 v[192:193], v[6:7], v[192:193]
	v_add_f32_e32 v192, v192, v194
	v_add_f32_e32 v192, v192, v193
	v_mul_f32_e32 v193, 0xbfb8aa3b, v199
	v_mul_f32_e32 v192, 0xbfb8aa3b, v192
	v_exp_f32_e32 v193, v193
	v_exp_f32_e32 v192, v192
	v_add_f32_e32 v193, 1.0, v193
	v_add_f32_e32 v192, 1.0, v192
	v_rcp_f32_e32 v193, v193
	v_rcp_f32_e32 v192, v192
	s_nop 0
	v_cvt_pk_bf16_f32 v198, v193, v192
	v_lshl_add_u64 v[192:193], v[4:5], 0, v[128:129]
	s_mov_b64 s[100:101], 0xc00
	v_lshl_add_u64 v[192:193], v[192:193], 0, s[100:101]
	global_store_dword v[192:193], v198, off
	v_lshlrev_b32_e32 v200, 16, v202
	v_lshlrev_b32_e32 v205, 16, v206
	v_lshlrev_b32_e32 v204, 16, v203
	v_pk_add_f32 v[204:205], v[204:205], v[200:201] op_sel_hi:[1,0] neg_lo:[0,1] neg_hi:[0,1]
	v_and_b32_e32 v202, 0xffff0000, v202
; DI unsigned pack2(float lo, float hi) { const f32x2 v = {lo, hi}; const bf16x2_t b = __builtin_convertvector(v, bf16x2_t); return __builtin_bit_cast(unsigned, b); }
; DI float lo2f(unsigned u) { return __uint_as_float(u << 16); }
; DI float hi2f(unsigned u) { return __uint_as_float(u & 0xffff0000u); }
; DI float sigmoidf_(float x) { return rcp_(1.0f + __expf(-x)); }
; DI void item_sg(const Params& p, int l, int L, int item, const bf16_t* __restrict__ z, bf16_t* __restrict__ sg) {
;     ...
;   for (int i = w; i < 256; i += 4) {
;     const int row = item * 256 + i;
;     const int t = row % L;
;     const bf16_t* zr = z + (size_t)row * ZC + 1664 + 2 * lane;
;     const unsigned c = *(const unsigned*)zr;
;     const unsigned pv = (t > 0) ? *(const unsigned*)(zr - ZC) : 0u;
;     const unsigned nv = (t < L - 1) ? *(const unsigned*)(zr + ZC) : 0u;
;     const float ca = lo2f(c), cb = hi2f(c);
;     const float ga = ca + m0a * (lo2f(pv) - ca) + m1a * (lo2f(nv) - ca);
;     const float gb = cb + m0b * (hi2f(pv) - cb) + m1b * (hi2f(nv) - cb);
;     *(unsigned*)(sg + (size_t)row * 128 + 2 * lane) = pack2(sigmoidf_(ga), sigmoidf_(gb));
;   }
	v_pk_mul_f32 v[204:205], v[0:1], v[204:205]
	v_and_b32_e32 v201, 0xffff0000, v206
	v_add_f32_e32 v200, v204, v200
	v_add_f32_e32 v207, v200, v205
	v_and_b32_e32 v200, 0xffff0000, v203
	v_pk_add_f32 v[200:201], v[200:201], v[202:203] op_sel_hi:[1,0] neg_lo:[0,1] neg_hi:[0,1]
	v_pk_mul_f32 v[200:201], v[6:7], v[200:201]
	v_add_f32_e32 v200, v200, v202
	v_add_f32_e32 v200, v200, v201
	v_mul_f32_e32 v201, 0xbfb8aa3b, v207
	v_mul_f32_e32 v200, 0xbfb8aa3b, v200
	v_exp_f32_e32 v201, v201
	v_exp_f32_e32 v200, v200
	v_add_f32_e32 v201, 1.0, v201
	v_add_f32_e32 v200, 1.0, v200
	v_rcp_f32_e32 v201, v201
	v_rcp_f32_e32 v200, v200
	s_nop 0
	v_cvt_pk_bf16_f32 v206, v201, v200
	v_lshl_add_u64 v[200:201], v[4:5], 0, v[128:129]
	s_mov_b64 s[100:101], 0x1000
	v_lshl_add_u64 v[200:201], v[200:201], 0, s[100:101]
	global_store_dword v[200:201], v206, off
	v_lshlrev_b32_e32 v228, 16, v230
	v_lshlrev_b32_e32 v233, 16, v234
	v_lshlrev_b32_e32 v232, 16, v231
	v_pk_add_f32 v[232:233], v[232:233], v[228:229] op_sel_hi:[1,0] neg_lo:[0,1] neg_hi:[0,1]
	v_and_b32_e32 v230, 0xffff0000, v230
	v_pk_mul_f32 v[232:233], v[0:1], v[232:233]
	v_and_b32_e32 v229, 0xffff0000, v234
	v_add_f32_e32 v228, v232, v228
	v_add_f32_e32 v235, v228, v233
	v_and_b32_e32 v228, 0xffff0000, v231
	v_pk_add_f32 v[228:229], v[228:229], v[230:231] op_sel_hi:[1,0] neg_lo:[0,1] neg_hi:[0,1]
	v_pk_mul_f32 v[228:229], v[6:7], v[228:229]
	v_add_f32_e32 v228, v228, v230
	v_add_f32_e32 v228, v228, v229
	v_mul_f32_e32 v229, 0xbfb8aa3b, v235
	v_mul_f32_e32 v228, 0xbfb8aa3b, v228
	v_exp_f32_e32 v229, v229
	v_exp_f32_e32 v228, v228
	v_add_f32_e32 v229, 1.0, v229
	v_add_f32_e32 v228, 1.0, v228
	v_rcp_f32_e32 v229, v229
	v_rcp_f32_e32 v228, v228
	s_nop 0
	v_cvt_pk_bf16_f32 v234, v229, v228
	v_lshl_add_u64 v[228:229], v[4:5], 0, v[128:129]
	s_mov_b64 s[100:101], 0x1400
	v_lshl_add_u64 v[228:229], v[228:229], 0, s[100:101]
	global_store_dword v[228:229], v234, off
	v_lshlrev_b32_e32 v236, 16, v238
	v_lshlrev_b32_e32 v241, 16, v242
	v_lshlrev_b32_e32 v240, 16, v239
	v_pk_add_f32 v[240:241], v[240:241], v[236:237] op_sel_hi:[1,0] neg_lo:[0,1] neg_hi:[0,1]
	v_and_b32_e32 v238, 0xffff0000, v238
	v_pk_mul_f32 v[240:241], v[0:1], v[240:241]
	v_and_b32_e32 v237, 0xffff0000, v242
	v_add_f32_e32 v236, v240, v236
	v_add_f32_e32 v243, v236, v241
	v_and_b32_e32 v236, 0xffff0000, v239
	v_pk_add_f32 v[236:237], v[236:237], v[238:239] op_sel_hi:[1,0] neg_lo:[0,1] neg_hi:[0,1]
	v_pk_mul_f32 v[236:237], v[6:7], v[236:237]
	v_add_f32_e32 v236, v236, v238
	v_add_f32_e32 v236, v236, v237
	v_mul_f32_e32 v237, 0xbfb8aa3b, v243
	v_mul_f32_e32 v236, 0xbfb8aa3b, v236
	v_exp_f32_e32 v237, v237
	v_exp_f32_e32 v236, v236
	v_add_f32_e32 v237, 1.0, v237
	v_add_f32_e32 v236, 1.0, v236
	v_rcp_f32_e32 v237, v237
	v_rcp_f32_e32 v236, v236
	s_nop 0
	v_cvt_pk_bf16_f32 v242, v237, v236
	v_lshl_add_u64 v[236:237], v[4:5], 0, v[128:129]
	s_mov_b64 s[100:101], 0x1800
	v_lshl_add_u64 v[236:237], v[236:237], 0, s[100:101]
	global_store_dword v[236:237], v242, off
	v_lshlrev_b32_e32 v244, 16, v246
	v_lshlrev_b32_e32 v249, 16, v250
	v_lshlrev_b32_e32 v248, 16, v247
	v_pk_add_f32 v[248:249], v[248:249], v[244:245] op_sel_hi:[1,0] neg_lo:[0,1] neg_hi:[0,1]
	v_and_b32_e32 v246, 0xffff0000, v246
	v_pk_mul_f32 v[248:249], v[0:1], v[248:249]
	v_and_b32_e32 v245, 0xffff0000, v250
	v_add_f32_e32 v244, v248, v244
	v_add_f32_e32 v251, v244, v249
	v_and_b32_e32 v244, 0xffff0000, v247
	v_pk_add_f32 v[244:245], v[244:245], v[246:247] op_sel_hi:[1,0] neg_lo:[0,1] neg_hi:[0,1]
	v_pk_mul_f32 v[244:245], v[6:7], v[244:245]
	v_add_f32_e32 v244, v244, v246
	v_add_f32_e32 v244, v244, v245
	v_mul_f32_e32 v245, 0xbfb8aa3b, v251
	v_mul_f32_e32 v244, 0xbfb8aa3b, v244
	v_exp_f32_e32 v245, v245
	v_exp_f32_e32 v244, v244
	v_add_f32_e32 v245, 1.0, v245
	v_add_f32_e32 v244, 1.0, v244
	v_rcp_f32_e32 v245, v245
	v_rcp_f32_e32 v244, v244
	s_nop 0
	v_cvt_pk_bf16_f32 v250, v245, v244
	v_lshl_add_u64 v[244:245], v[4:5], 0, v[128:129]
	s_mov_b64 s[100:101], 0x1c00
	v_lshl_add_u64 v[244:245], v[244:245], 0, s[100:101]
	global_store_dword v[244:245], v250, off
	s_movk_i32 s8, 0xdf
	v_cmp_lt_u32_e32 vcc, s8, v11
	s_mov_b64 s[100:101], 0x34000
	v_lshl_add_u64 v[2:3], v[2:3], 0, s[100:101]
	s_or_b64 s[6:7], vcc, s[6:7]
	v_add_u32_e32 v11, 32, v11
	s_mov_b64 s[100:101], 0x2000
	v_lshl_add_u64 v[4:5], v[4:5], 0, s[100:101]
	s_andn2_b64 exec, exec, s[6:7]
	s_cbranch_execz .LBB0_410
	s_branch .LBB0_406
